# mixer units remapped so 32 consecutive units share an XCD; plus rsl cache and early L1 invalidate
# speedup vs baseline: 1.0132x; 1.0132x over previous
; #define LAS __attribute__((address_space(3)))
; #define INP(k) ldptr(PT, (k))
; __device__ __forceinline__ void mixer_unit(LAS unsigned char* lds, int unit, const bf16* P, bf16* Y, const float* conv_w, const float* sgu_norm, const float* sgu_w, const float* sgu_b, int tid, int wave, int lane) {
;     const int t0 = unit * 64;
;     asm volatile("" : "+v"(tid), "+v"(lane));
;     LAS bf16* vnT = (LAS bf16*)lds;
;     LAS float* tile = (LAS float*)(lds + 69632);
;     LAS float* sm_ss = (LAS float*)(lds + 69632 + 66560);
;     {
;         const int hd = wave, r = lane & 31, h = lane >> 5;
;         const int pr = (r & 0x13) | ((r & 4) << 1) | ((r & 8) >> 1);
;         LAS bf16* Vr = (LAS bf16*)(lds + wave * 6144);
;         const LAS bf16* vtb = Vr + (8 * h + ((lane & 15) >> 2)) * 96 + 16 * ((lane >> 4) & 1) + 4 * (lane & 3);
;         f32x16 oacc[2][2];
;         bf16x8 kfn[4]; v4u vvn[4];
;         { const bf16* kp = P + (size_t)(t0 + 32 + pr) * NIN + 1792 + hd * 64 + 8 * h;
; #pragma unroll
;           for (int ks = 0; ks < 4; ++ks) kfn[ks] = *(const __attribute__((address_space(1))) bf16x8*)(kp + 16 * ks);
; #pragma unroll
;           for (int i = 0; i < 4; ++i) vvn[i] = *(const __attribute__((address_space(1))) v4u*)(P + (size_t)(t0 + 32 + (lane >> 3) + 8 * i) * NIN + 2304 + hd * 64 + 8 * (lane & 7)); }
;         bf16x8 kf2[4]; v4u vv2[4];
;         { const bf16* kp = P + (size_t)(t0 + pr) * NIN + 1792 + hd * 64 + 8 * h;
; #pragma unroll
;           for (int ks = 0; ks < 4; ++ks) kf2[ks] = *(const __attribute__((address_space(1))) bf16x8*)(kp + 16 * ks);
; #pragma unroll
;           for (int i = 0; i < 4; ++i) vv2[i] = *(const __attribute__((address_space(1))) v4u*)(P + (size_t)(t0 + (lane >> 3) + 8 * i) * NIN + 2304 + hd * 64 + 8 * (lane & 7)); }
; __global__ void __launch_bounds__(NTHR, 2) hybrid_fwd(Args args) {
;     ...
;             for (int u = bx; u < S / 64; u += G)
;                 mixer_unit(lds, u, P, Y, INP(3) + l * 3 * 256, INP(4) + l * 256, INP(5) + (size_t)l * 4 * 128 * 128, INP(6) + l * 4 * 128, tid, wave, lane);
.LBB0_153:
	s_andn2_b64 vcc, exec, s[0:1]
	s_cbranch_vccnz .LBB0_314
	s_and_b32 s0, 0xffff, s5
	s_cmp_gt_i32 s0, 0
	s_mov_b64 s[0:1], -1
	s_cbranch_scc0 .LBB0_294
	v_readlane_b32 s8, v253, 26
	v_readlane_b32 s12, v253, 30
	v_readlane_b32 s13, v253, 31
	v_readlane_b32 s14, v253, 32
	v_readlane_b32 s15, v253, 33
	v_readlane_b32 s20, v253, 38
	v_readlane_b32 s21, v253, 39
	v_readlane_b32 s22, v253, 40
	v_readlane_b32 s23, v253, 41
	s_mov_b64 s[12:13], s[20:21]
	s_mov_b64 s[14:15], s[22:23]
	s_mov_b64 s[0:1], s[14:15]
	s_mov_b64 s[6:7], s[12:13]
	s_andn2_b64 vcc, exec, s[88:89]
	v_readlane_b32 s9, v253, 27
	v_readlane_b32 s10, v253, 28
	v_readlane_b32 s11, v253, 29
	v_readlane_b32 s16, v253, 34
	v_readlane_b32 s17, v253, 35
	v_readlane_b32 s18, v253, 36
	v_readlane_b32 s19, v253, 37
	s_cbranch_vccnz .LBB0_293
	s_add_u32 s22, s0, 0x8300000
	s_addc_u32 s23, s1, 0
	s_add_u32 s84, s0, 0xdb00000
	v_readlane_b32 s6, v255, 8
	s_addc_u32 s85, s1, 0
	s_mul_i32 s2, s6, 0x300
	s_lshl_b32 s5, s6, 8
	s_lshl_b32 s76, s6, 18
	s_lshl_b32 s6, s6, 9
	s_add_u32 s86, s0, 0xdb00200
	s_addc_u32 s87, s1, 0
	s_add_u32 s20, s22, s98
	s_addc_u32 s21, s23, s99
	s_add_u32 s92, s84, s98
	v_readlane_b32 s0, v252, 10
	s_addc_u32 s93, s85, s99
	s_lshl_b32 s0, s0, 1
	s_add_u32 s0, s22, s0
	s_addc_u32 s1, s23, 0
	v_writelane_b32 v255, s0, 10
	s_lshl_b32 s83, s2, 2
	v_readlane_b32 s95, v253, 61
	v_writelane_b32 v255, s1, 11
	s_lshl_b32 s0, s5, 2
	v_writelane_b32 v255, s0, 12
	s_lshl_b32 s0, s6, 2
	v_writelane_b32 v255, s0, 13
	s_mov_b32 s2, s27
	s_cmp_lg_u32 s96, 0x100
	s_cbranch_scc1 .Lmix_noremap
	s_and_b32 s0, s27, 7
	s_lshl_b32 s0, s0, 5
	s_lshr_b32 s2, s27, 3
	s_add_i32 s2, s2, s0
	s_sub_i32 s0, s2, s27
	s_lshl_b32 s0, s0, 6
	s_add_i32 s95, s95, s0
.Lmix_noremap:
.LBB0_157:
	v_readlane_b32 s0, v254, 4
	v_mov_b32_e32 v240, v218
	v_mov_b32_e32 v225, v219
	v_mov_b32_e32 v0, s0
	v_readlane_b32 s0, v254, 5
	ds_read_b32 v17, v0
	s_lshl_b32 s28, s2, 6
	v_mov_b32_e32 v0, s0
	v_readlane_b32 s0, v254, 6
	ds_read_b32 v112, v0
	v_mov_b64_e32 v[4:5], s[20:21]
	v_mov_b32_e32 v0, s0
	v_readlane_b32 s0, v254, 7
	ds_read_b32 v113, v0
	v_readlane_b32 s1, v252, 38
	v_mov_b32_e32 v0, s0
	v_readlane_b32 s0, v254, 8
	ds_read_b32 v114, v0
	s_waitcnt lgkmcnt(3)
	v_readfirstlane_b32 s89, v17
	v_mov_b32_e32 v0, s0
	v_readlane_b32 s0, v254, 9
	ds_read_b32 v115, v0
	s_waitcnt lgkmcnt(3)
	v_readfirstlane_b32 s33, v112
	v_mov_b32_e32 v0, s0
	v_readlane_b32 s0, v254, 10
	ds_read_b32 v116, v0
	s_waitcnt lgkmcnt(3)
	v_readfirstlane_b32 s25, v113
	v_mov_b32_e32 v0, s0
	v_readlane_b32 s0, v254, 11
	ds_read_b32 v117, v0
	s_waitcnt lgkmcnt(3)
	v_readfirstlane_b32 s88, v114
	v_mov_b32_e32 v0, s0
	ds_read_b32 v118, v0
	s_or_b32 s0, s28, 32
	v_lshlrev_b32_e32 v1, 1, v225
	v_lshrrev_b32_e32 v2, 1, v225
	v_ashrrev_i32_e32 v226, 5, v225
	v_and_b32_e32 v0, 19, v225
	v_and_b32_e32 v1, 8, v1
	v_and_b32_e32 v2, 4, v2
	v_or3_b32 v211, v1, v0, v2
	v_lshlrev_b32_e32 v206, 3, v226
	v_or_b32_e32 v0, s0, v211
	v_ashrrev_i32_e32 v207, 31, v206
	v_mad_i64_i32 v[0:1], s[6:7], v0, s90, v[4:5]
	v_lshlrev_b64 v[208:209], 1, v[206:207]
	v_lshl_add_u64 v[6:7], v[0:1], 0, v[208:209]
	v_ashrrev_i32_e32 v241, 3, v225
	global_load_dwordx4 v[0:3], v[6:7], off offset:3584
	global_load_dwordx4 v[18:21], v[6:7], off offset:3616
	global_load_dwordx4 v[22:25], v[6:7], off offset:3648
	global_load_dwordx4 v[26:29], v[6:7], off offset:3680
	v_add_u32_e32 v14, s0, v241
	v_lshlrev_b32_e32 v16, 3, v225
	v_mov_b64_e32 v[6:7], s[22:23]
	v_and_b32_e32 v10, 56, v16
	v_mad_i64_i32 v[8:9], s[6:7], v14, s90, v[6:7]
	v_lshl_add_u64 v[8:9], v[8:9], 0, s[98:99]
	v_lshlrev_b32_e32 v192, 1, v10
	v_add_u32_e32 v10, 8, v14
	v_lshl_add_u64 v[8:9], v[8:9], 0, v[192:193]
	v_mad_i64_i32 v[10:11], s[6:7], v10, s90, v[6:7]
	v_and_b32_e32 v224, 31, v225
	v_add_co_u32_e32 v8, vcc, s91, v8
	v_lshl_add_u64 v[10:11], v[10:11], 0, s[98:99]
	v_or_b32_e32 v12, s0, v224
	v_addc_co_u32_e32 v9, vcc, 0, v9, vcc
	v_lshl_add_u64 v[10:11], v[10:11], 0, v[192:193]
	v_mad_i64_i32 v[12:13], s[6:7], v12, s90, v[4:5]
	v_add_co_u32_e32 v10, vcc, s91, v10
	v_lshl_add_u64 v[12:13], v[12:13], 0, v[208:209]
	s_nop 0
	v_addc_co_u32_e32 v11, vcc, 0, v11, vcc
	global_load_dwordx4 v[36:39], v[12:13], off offset:2560
	global_load_dwordx4 v[40:43], v[8:9], off offset:512
	global_load_dwordx4 v[44:47], v[10:11], off offset:512
	v_add_u32_e32 v8, 16, v14
	v_mad_i64_i32 v[8:9], s[6:7], v8, s90, v[6:7]
	v_lshl_add_u64 v[8:9], v[8:9], 0, s[98:99]
	v_add_u32_e32 v10, 24, v14
	v_lshl_add_u64 v[8:9], v[8:9], 0, v[192:193]
	v_mad_i64_i32 v[10:11], s[6:7], v10, s90, v[6:7]
	v_add_co_u32_e32 v8, vcc, s91, v8
	v_lshl_add_u64 v[10:11], v[10:11], 0, s[98:99]
	s_nop 0
	v_addc_co_u32_e32 v9, vcc, 0, v9, vcc
	v_lshl_add_u64 v[10:11], v[10:11], 0, v[192:193]
	v_add_co_u32_e32 v10, vcc, s91, v10
	v_add_u32_e32 v14, s28, v241
	s_nop 0
	v_addc_co_u32_e32 v11, vcc, 0, v11, vcc
	global_load_dwordx4 v[48:51], v[8:9], off offset:512
	global_load_dwordx4 v[52:55], v[10:11], off offset:512
	v_or_b32_e32 v8, s28, v211
	v_mad_i64_i32 v[8:9], s[6:7], v8, s90, v[4:5]
	v_lshl_add_u64 v[30:31], v[8:9], 0, v[208:209]
	v_mad_i64_i32 v[8:9], s[6:7], v14, s90, v[6:7]
	v_lshl_add_u64 v[8:9], v[8:9], 0, s[98:99]
	v_add_u32_e32 v10, 8, v14
	v_lshl_add_u64 v[8:9], v[8:9], 0, v[192:193]
	v_mad_i64_i32 v[10:11], s[6:7], v10, s90, v[6:7]
	v_add_co_u32_e32 v8, vcc, s91, v8
; #define LAS __attribute__((address_space(3)))
; __device__ __forceinline__ void mixer_unit(LAS unsigned char* lds, int unit, const bf16* P, bf16* Y, const float* conv_w, const float* sgu_norm, const float* sgu_w, const float* sgu_b, int tid, int wave, int lane) {
;     ...
;         LAS bf16x8* Qs = (LAS bf16x8*)(lds + 49152 + wave * 8192);
; #pragma unroll
;         for (int ks = 0; ks < 4; ++ks) { Qs[ks * 64 + lane] = *(const __attribute__((address_space(1))) bf16x8*)(P + (size_t)(t0 + r) * NIN + 1280 + hd * 64 + 16 * ks + 8 * h); Qs[(4 + ks) * 64 + lane] = *(const __attribute__((address_space(1))) bf16x8*)(P + (size_t)(t0 + 32 + r) * NIN + 1280 + hd * 64 + 16 * ks + 8 * h); }
; #pragma unroll
;         for (int a = 0; a < 2; ++a)
; #pragma unroll
;             for (int b = 0; b < 2; ++b) oacc[a][b] = (f32x16){};
;         float lsA = 1.0f, lsB = 1.0f; bool actA = true, actB = true;
;     ...
;         for (int k0 = t0 + 32;; k0 -= 32) {
;             const bool doA = actA && (k0 <= t0);
;             f32x16 zB = {}, zA = {};
;             if (actB) {
; #pragma unroll
;                 for (int ks = 0; ks < 4; ++ks) zB = __builtin_amdgcn_mfma_f32_32x32x16_bf16(kfn[ks], Qs[(4 + ks) * 64 + lane], zB, 0, 0, 0); }
;             if (doA) {
; #pragma unroll
;                 for (int ks = 0; ks < 4; ++ks) zA = __builtin_amdgcn_mfma_f32_32x32x16_bf16(kfn[ks], Qs[ks * 64 + lane], zA, 0, 0, 0); }
; #pragma unroll
;             for (int i = 0; i < 4; ++i) { const int key = (lane >> 3) + 8 * i, c = lane & 7; *(LAS v4u*)(Vr + key * 96 + 8 * c) = vvn[i]; }
; #pragma unroll
;             for (int ks = 0; ks < 4; ++ks) kfn[ks] = kf2[ks];
; #pragma unroll
;             for (int i = 0; i < 4; ++i) vvn[i] = vv2[i];
;             if (k0 >= 64) { const bf16* kp = P + (size_t)(k0 - 64 + pr) * NIN + 1792 + hd * 64 + 8 * h;
; #pragma unroll
;                 for (int ks = 0; ks < 4; ++ks) kf2[ks] = *(const __attribute__((address_space(1))) bf16x8*)(kp + 16 * ks);
; #pragma unroll
;                 for (int i = 0; i < 4; ++i) vv2[i] = *(const __attribute__((address_space(1))) v4u*)(P + (size_t)(k0 - 64 + (lane >> 3) + 8 * i) * NIN + 2304 + hd * 64 + 8 * (lane & 7)); }
	v_lshl_add_u64 v[10:11], v[10:11], 0, s[98:99]
	s_nop 0
	v_addc_co_u32_e32 v9, vcc, 0, v9, vcc
	v_lshl_add_u64 v[10:11], v[10:11], 0, v[192:193]
	v_add_co_u32_e32 v10, vcc, s91, v10
	v_or_b32_e32 v210, s28, v224
	s_nop 0
	v_addc_co_u32_e32 v11, vcc, 0, v11, vcc
	global_load_dwordx4 v[64:67], v[8:9], off offset:512
	global_load_dwordx4 v[68:71], v[10:11], off offset:512
	global_load_dwordx4 v[56:59], v[12:13], off offset:2592
	v_mad_i64_i32 v[4:5], s[6:7], v210, s90, v[4:5]
	v_lshl_add_u64 v[4:5], v[4:5], 0, v[208:209]
	global_load_dwordx4 v[60:63], v[4:5], off offset:2560
	global_load_dwordx4 v[92:95], v[4:5], off offset:2592
	global_load_dwordx4 v[96:99], v[12:13], off offset:2624
	global_load_dwordx4 v[100:103], v[4:5], off offset:2624
	global_load_dwordx4 v[104:107], v[4:5], off offset:2656
	global_load_dwordx4 v[108:111], v[12:13], off offset:2656
	v_add_u32_e32 v8, 16, v14
	v_mad_i64_i32 v[8:9], s[6:7], v8, s90, v[6:7]
	v_lshl_add_u64 v[8:9], v[8:9], 0, s[98:99]
	v_lshl_add_u64 v[8:9], v[8:9], 0, v[192:193]
	v_add_co_u32_e32 v4, vcc, s91, v8
	v_add_u32_e32 v8, 24, v14
	v_mad_i64_i32 v[6:7], s[6:7], v8, s90, v[6:7]
	v_lshl_add_u64 v[6:7], v[6:7], 0, s[98:99]
	v_addc_co_u32_e32 v5, vcc, 0, v9, vcc
	v_lshl_add_u64 v[6:7], v[6:7], 0, v[192:193]
	v_add_co_u32_e32 v6, vcc, s91, v6
	v_lshl_add_u32 v242, v225, 4, s1
	s_nop 0
	v_addc_co_u32_e32 v7, vcc, 0, v7, vcc
	global_load_dwordx4 v[72:75], v[4:5], off offset:512
	global_load_dwordx4 v[76:79], v[6:7], off offset:512
	global_load_dwordx4 v[32:35], v[30:31], off offset:3584
	global_load_dwordx4 v[84:87], v[30:31], off offset:3616
	global_load_dwordx4 v[88:91], v[30:31], off offset:3648
	global_load_dwordx4 v[80:83], v[30:31], off offset:3680
	s_waitcnt vmcnt(19)
	v_mfma_f32_32x32x16_bf16 v[0:15], v[0:3], v[36:39], 0
	s_movk_i32 s1, 0xc0
	s_waitcnt lgkmcnt(3)
	v_readfirstlane_b32 s72, v115
	s_waitcnt lgkmcnt(2)
	v_readfirstlane_b32 s73, v116
	s_waitcnt lgkmcnt(1)
	v_readfirstlane_b32 s29, v117
	s_waitcnt lgkmcnt(0)
	v_readfirstlane_b32 s24, v118
	s_waitcnt vmcnt(11)
	ds_write_b128 v242, v[60:63] offset:49152
	ds_write_b128 v242, v[36:39] offset:53248
	v_mfma_f32_32x32x16_bf16 v[0:15], v[18:21], v[56:59], v[0:15]
	s_waitcnt vmcnt(10)
	ds_write_b128 v242, v[92:95] offset:50176
	ds_write_b128 v242, v[56:59] offset:54272
	s_waitcnt vmcnt(8)
	ds_write_b128 v242, v[100:103] offset:51200
	ds_write_b128 v242, v[96:99] offset:55296
	s_waitcnt vmcnt(7)
	ds_write_b128 v242, v[104:107] offset:52224
	s_waitcnt vmcnt(6)
	ds_write_b128 v242, v[108:111] offset:56320
	v_add_u32_e32 v17, s77, v192
	v_mul_lo_u32 v18, v241, s1
	v_mov_b64_e32 v[102:103], v[70:71]
	v_mfma_f32_32x32x16_bf16 v[0:15], v[22:25], v[96:99], v[0:15]
	v_mov_b64_e32 v[98:99], v[66:67]
	v_add_u32_e32 v243, v17, v18
	s_cmp_lt_i32 s0, 64
	v_mov_b64_e32 v[96:97], v[64:65]
	v_mov_b64_e32 v[100:101], v[68:69]
	ds_write_b128 v243, v[40:43]
	ds_write_b128 v243, v[44:47] offset:1536
	ds_write_b128 v243, v[48:51] offset:3072
	ds_write_b128 v243, v[52:55] offset:4608
	s_waitcnt vmcnt(5)
	v_mov_b64_e32 v[106:107], v[74:75]
	v_mfma_f32_32x32x16_bf16 v[0:15], v[26:29], v[108:111], v[0:15]
	s_waitcnt vmcnt(4)
	v_mov_b64_e32 v[110:111], v[78:79]
	s_waitcnt vmcnt(3)
	v_mov_b64_e32 v[126:127], v[34:35]
	s_waitcnt vmcnt(2)
	v_mov_b64_e32 v[118:119], v[86:87]
	s_waitcnt vmcnt(1)
	v_mov_b64_e32 v[122:123], v[90:91]
	s_waitcnt vmcnt(0)
	v_mov_b64_e32 v[114:115], v[82:83]
	v_mov_b64_e32 v[104:105], v[72:73]
	v_mov_b64_e32 v[108:109], v[76:77]
	v_mov_b64_e32 v[124:125], v[32:33]
	v_mov_b64_e32 v[116:117], v[84:85]
	v_mov_b64_e32 v[120:121], v[88:89]
	v_mov_b64_e32 v[112:113], v[80:81]
	s_cbranch_scc1 .LBB0_159
	s_sub_i32 s5, s28, 32
	v_or_b32_e32 v17, s5, v211
	v_mov_b64_e32 v[18:19], s[20:21]
	v_mad_u64_u32 v[18:19], s[0:1], v17, s90, v[18:19]
	v_lshl_add_u64 v[18:19], v[206:207], 1, v[18:19]
	global_load_dwordx4 v[124:127], v[18:19], off offset:3584
	global_load_dwordx4 v[116:119], v[18:19], off offset:3616
	global_load_dwordx4 v[120:123], v[18:19], off offset:3648
	global_load_dwordx4 v[112:115], v[18:19], off offset:3680
	v_add_u32_e32 v17, s5, v241
	v_mov_b64_e32 v[18:19], s[22:23]
	v_mad_i64_i32 v[20:21], s[0:1], v17, s90, v[18:19]
	v_lshl_add_u64 v[20:21], v[20:21], 0, s[98:99]
	v_add_u32_e32 v22, 8, v17
	v_lshl_add_u64 v[20:21], v[20:21], 0, v[192:193]
	v_mad_i64_i32 v[22:23], s[0:1], v22, s90, v[18:19]
	v_add_co_u32_e32 v20, vcc, s91, v20
	v_lshl_add_u64 v[22:23], v[22:23], 0, s[98:99]
	s_nop 0
	v_addc_co_u32_e32 v21, vcc, 0, v21, vcc
	v_lshl_add_u64 v[22:23], v[22:23], 0, v[192:193]
	v_add_co_u32_e32 v22, vcc, s91, v22
	s_nop 1
	v_addc_co_u32_e32 v23, vcc, 0, v23, vcc
	global_load_dwordx4 v[96:99], v[20:21], off offset:512
	global_load_dwordx4 v[100:103], v[22:23], off offset:512
	v_add_u32_e32 v20, 16, v17
	v_mad_i64_i32 v[20:21], s[0:1], v20, s90, v[18:19]
	v_lshl_add_u64 v[20:21], v[20:21], 0, s[98:99]
	v_add_u32_e32 v17, 24, v17
	v_lshl_add_u64 v[20:21], v[20:21], 0, v[192:193]
	v_mad_i64_i32 v[18:19], s[0:1], v17, s90, v[18:19]
	v_add_co_u32_e32 v20, vcc, 0x1000, v20
	v_lshl_add_u64 v[18:19], v[18:19], 0, s[98:99]
	s_nop 0
	v_addc_co_u32_e32 v21, vcc, 0, v21, vcc
	v_lshl_add_u64 v[18:19], v[18:19], 0, v[192:193]
	v_add_co_u32_e32 v18, vcc, 0x1000, v18
	s_nop 1
	v_addc_co_u32_e32 v19, vcc, 0, v19, vcc
	global_load_dwordx4 v[104:107], v[20:21], off offset:512
	global_load_dwordx4 v[108:111], v[18:19], off offset:512
